# rebalance GLA scan chains across virtual blocks (prompt-chain blocks take no sample chains) + g3 LDS-staged wide stores + ds_read_b64 split
# speedup vs baseline: 1.0036x; 1.0036x over previous
; DI void phase_attn_scan(const P& p, char* smem_block, int rep) {
;     ...
;     for (int it = VB; it < NSCAN_P + NSCAN_S; it += VN) {
;       if (it < NSCAN_P) {
;         int sub = it & 15, ch = it >> 4;
;         gla_scan_item(p, 0, 256, ch >> 1, ch & 1, sub);
;       } else {
;         int i2 = it - NSCAN_P;
;         int sub = i2 & 15, ch = i2 >> 4;
;         int sq = ch >> 3;
;         gla_scan_item(p, 256 + sq * 32, 32, (ch >> 1) & 3, ch & 1, sub);
;       }
;     }
.LBB0_484:
	s_mov_b64 s[6:7], s[0:1]
	v_mov_b32_e32 v1, 0
	global_load_dwordx2 v[2:3], v1, s[6:7] offset:240
	v_lshrrev_b32_e32 v0, 8, v210
	s_movk_i32 s8, 0x1080
	s_add_u32 s6, s0, 0x100
	v_lshl_add_u32 v105, s2, 1, v0
	s_addc_u32 s7, s1, 0
	v_cmp_gt_i32_e32 vcc, s8, v105
	v_lshlrev_b32_e32 v104, 3, v210
	s_waitcnt vmcnt(0)
	v_readfirstlane_b32 s9, v3
	v_readfirstlane_b32 s8, v2
	s_and_saveexec_b64 s[10:11], vcc
	s_cbranch_execz .LBB0_492
	s_load_dword s24, s[6:7], 0x0
	v_lshlrev_b32_e32 v0, 1, v210
	v_and_b32_e32 v106, 0x1fe, v0
	v_and_b32_e32 v0, 0xf8, v104
	s_add_u32 s12, s8, 0x2ab00000
	v_lshl_add_u64 v[2:3], s[8:9], 0, v[0:1]
	s_mov_b64 s[16:17], 0x34b00000
	s_addc_u32 s13, s9, 0
	v_lshl_add_u64 v[2:3], v[2:3], 0, s[16:17]
	s_waitcnt lgkmcnt(0)
	s_lshl_b32 s26, s24, 1
	s_add_i32 s26, s26, 0xffffff80
	v_mov_b32_e32 v243, 0x2000
	v_cmp_gt_u32_e32 vcc, 0x80, v105
	v_mov_b32_e32 v242, s26
	v_cndmask_b32_e32 v243, v242, v243, vcc
	s_mov_b64 s[16:17], 0
	s_movk_i32 s27, 0x7f
	s_movk_i32 s28, 0x1e00
	s_movk_i32 s29, 0x107f
	s_branch .LBB0_487
.LBB0_486:
	s_or_b64 exec, exec, s[24:25]
	v_add_u32_e32 v105, v243, v105
	v_cmp_lt_i32_e32 vcc, s29, v105
	s_or_b64 s[16:17], vcc, s[16:17]
	s_andn2_b64 exec, exec, s[16:17]
	s_cbranch_execz .LBB0_492
